# E-GEMM also skips the zero-weight half of each remaining K-tile (block-diagonal composed S5 weight): 16 instead of 32 MFMAs per barrier interval
# baseline (speedup 1.0000x reference)
; #define PG8_STAGE(bufoff, gbase, voff) do { _Pragma("unroll") for (int _i = 0; _i < 2; ++_i) \
;         __builtin_amdgcn_global_load_lds((const unsigned*)((const char*)(gbase) + (voff)[_i]), (LAS unsigned*)(lds + (bufoff) + ldsw + _i * 8192), 16, 0, 0); } while (0)
; #define PG8_LDA(dst, b, h) do { _Pragma("unroll") for (int m = 0; m < 4; ++m) _Pragma("unroll") for (int k = 0; k < 2; ++k) dst[m][k] = *(const LAS bf16x8*)(lds + PG8_SA(b, h) + aoff + m * 2048 + k * 1024); } while (0)
; #define PG8_LDB(dst, b, h) do { _Pragma("unroll") for (int n = 0; n < 2; ++n) _Pragma("unroll") for (int k = 0; k < 2; ++k) dst[n][k] = *(const LAS bf16x8*)(lds + PG8_SB(b, h) + boff + n * 2048 + k * 1024); } while (0)
; #define PG8_MMA(ai, bj, At, Bt) do { __builtin_amdgcn_s_setprio(1); _Pragma("unroll") for (int m = 0; m < 4; ++m) _Pragma("unroll") for (int n = 0; n < 2; ++n) _Pragma("unroll") for (int k = 0; k < 2; ++k) \
;         acc[ai][bj][m][n] = __builtin_amdgcn_mfma_f32_16x16x32_bf16(Bt[n][k], At[m][k], acc[ai][bj][m][n], 0, 0, 0); __builtin_amdgcn_s_setprio(0); } while (0)
; #define PG8_WAIT_V(n) asm volatile("s_waitcnt vmcnt(" #n ")" ::: "memory")
; #define PG8_WAIT_L(n) asm volatile("s_waitcnt lgkmcnt(" #n ")" ::: "memory")
; #define PG8_BAR __builtin_amdgcn_s_barrier()
; #define PG8_SCHED __builtin_amdgcn_sched_barrier(0)
; template <class Epi>
; __device__ __forceinline__ void gemm_phase(LAS unsigned char* lds, const Gemm g, const int G, const int cidx, const int tid, const Epi& E) {
;     ...
;             PG8_LDB(B0, 0, 0); PG8_LDB(B1, 0, 1); PG8_SCHED; PG8_LDA(At, 0, 0); PG8_STAGE(PG8_SA(1, 1), a1 + hstepA, voffA);
;             PG8_WAIT_V(8); PG8_WAIT_L(0); PG8_BAR; PG8_MMA(0, 0, At, B0); PG8_MMA(0, 1, At, B1); PG8_BAR; PG8_SCHED;
.LBB0_509:
	s_cmp_eq_u32 s92, 0
	s_cselect_b32 s66, 1, 0
	s_lshl_b32 s66, s66, 8
	s_add_i32 s66, s66, 0x100
	s_add_u32 s16, s14, s66
	s_addc_u32 s17, s15, 0
	s_add_i32 s66, 0, 0x10000
	s_cmp_eq_u32 s92, 4
	s_cselect_b32 s53, s1, s17
	s_cselect_b32 s52, s0, s16
	v_add_u32_e32 v150, s66, v144
	s_cselect_b32 s19, s13, s65
	s_cselect_b32 s18, s12, s64
	s_add_i32 s67, 0, 0x14000
	ds_read_b128 v[138:141], v150
	ds_read_b128 v[146:149], v150 offset:1024
	ds_read_b128 v[164:167], v150 offset:2048
	ds_read_b128 v[168:171], v150 offset:3072
	v_add_u32_e32 v150, s67, v144
	ds_read_b128 v[172:175], v150
	ds_read_b128 v[176:179], v150 offset:1024
	ds_read_b128 v[180:183], v150 offset:2048
	ds_read_b128 v[184:187], v150 offset:3072
	v_lshl_add_u64 v[150:151], s[14:15], 0, v[134:135]
	s_add_i32 m0, s25, 0xc000
	ds_read_b128 v[188:191], v145
	ds_read_b128 v[210:213], v145 offset:1024
	ds_read_b128 v[214:217], v145 offset:2048
	ds_read_b128 v[218:221], v145 offset:3072
	ds_read_b128 v[222:225], v145 offset:4096
	ds_read_b128 v[226:229], v145 offset:5120
	ds_read_b128 v[230:233], v145 offset:6144
	ds_read_b128 v[234:237], v145 offset:7168
	global_load_lds_dwordx4 v[150:151], off
	v_lshl_add_u64 v[150:151], s[14:15], 0, v[136:137]
	s_add_i32 m0, s25, 0xe000
	s_nop 0
	global_load_lds_dwordx4 v[150:151], off
	s_waitcnt vmcnt(8)
	s_waitcnt lgkmcnt(0)
	s_barrier
	s_setprio 1
	s_waitcnt lgkmcnt(0)
	s_cmp_gt_i32 s92, 0
	s_cbranch_scc1 .Lez_0
	v_mfma_f32_16x16x32_bf16 v[124:127], v[138:141], v[188:191], v[124:127]
	v_mfma_f32_16x16x32_bf16 v[120:123], v[164:167], v[188:191], v[120:123]
	v_mfma_f32_16x16x32_bf16 v[108:111], v[138:141], v[214:217], v[108:111]
	v_mfma_f32_16x16x32_bf16 v[104:107], v[164:167], v[214:217], v[104:107]
	v_mfma_f32_16x16x32_bf16 v[92:95], v[138:141], v[222:225], v[92:95]
	v_mfma_f32_16x16x32_bf16 v[88:91], v[164:167], v[222:225], v[88:91]
	v_mfma_f32_16x16x32_bf16 v[76:79], v[138:141], v[230:233], v[76:79]
	v_mfma_f32_16x16x32_bf16 v[72:75], v[164:167], v[230:233], v[72:75]
	v_mfma_f32_16x16x32_bf16 v[124:127], v[146:149], v[210:213], v[124:127]
	v_mfma_f32_16x16x32_bf16 v[120:123], v[168:171], v[210:213], v[120:123]
	v_mfma_f32_16x16x32_bf16 v[108:111], v[146:149], v[218:221], v[108:111]
	v_mfma_f32_16x16x32_bf16 v[104:107], v[168:171], v[218:221], v[104:107]
	v_mfma_f32_16x16x32_bf16 v[92:95], v[146:149], v[226:229], v[92:95]
	v_mfma_f32_16x16x32_bf16 v[88:91], v[168:171], v[226:229], v[88:91]
	v_mfma_f32_16x16x32_bf16 v[76:79], v[146:149], v[234:237], v[76:79]
	v_mfma_f32_16x16x32_bf16 v[72:75], v[168:171], v[234:237], v[72:75]
.Lez_0:
	s_setprio 0
	s_setprio 1
	s_cmp_lt_i32 s92, 2
	s_cbranch_scc1 .Lez_1
	v_mfma_f32_16x16x32_bf16 v[116:119], v[172:175], v[188:191], v[116:119]
	v_mfma_f32_16x16x32_bf16 v[112:115], v[180:183], v[188:191], v[112:115]
	v_mfma_f32_16x16x32_bf16 v[100:103], v[172:175], v[214:217], v[100:103]
	v_mfma_f32_16x16x32_bf16 v[96:99], v[180:183], v[214:217], v[96:99]
	v_mfma_f32_16x16x32_bf16 v[84:87], v[172:175], v[222:225], v[84:87]
	v_mfma_f32_16x16x32_bf16 v[80:83], v[180:183], v[222:225], v[80:83]
	v_mfma_f32_16x16x32_bf16 v[68:71], v[172:175], v[230:233], v[68:71]
	v_mfma_f32_16x16x32_bf16 v[64:67], v[180:183], v[230:233], v[64:67]
	v_mfma_f32_16x16x32_bf16 v[116:119], v[176:179], v[210:213], v[116:119]
	v_mfma_f32_16x16x32_bf16 v[112:115], v[184:187], v[210:213], v[112:115]
	v_mfma_f32_16x16x32_bf16 v[100:103], v[176:179], v[218:221], v[100:103]
	v_mfma_f32_16x16x32_bf16 v[96:99], v[184:187], v[218:221], v[96:99]
	v_mfma_f32_16x16x32_bf16 v[84:87], v[176:179], v[226:229], v[84:87]
	v_mfma_f32_16x16x32_bf16 v[80:83], v[184:187], v[226:229], v[80:83]
	v_mfma_f32_16x16x32_bf16 v[68:71], v[176:179], v[234:237], v[68:71]
	v_mfma_f32_16x16x32_bf16 v[64:67], v[184:187], v[234:237], v[64:67]
; #define PG8_STAGE(bufoff, gbase, voff) do { _Pragma("unroll") for (int _i = 0; _i < 2; ++_i) \
;         __builtin_amdgcn_global_load_lds((const unsigned*)((const char*)(gbase) + (voff)[_i]), (LAS unsigned*)(lds + (bufoff) + ldsw + _i * 8192), 16, 0, 0); } while (0)
; #define PG8_LDA(dst, b, h) do { _Pragma("unroll") for (int m = 0; m < 4; ++m) _Pragma("unroll") for (int k = 0; k < 2; ++k) dst[m][k] = *(const LAS bf16x8*)(lds + PG8_SA(b, h) + aoff + m * 2048 + k * 1024); } while (0)
; #define PG8_LDB(dst, b, h) do { _Pragma("unroll") for (int n = 0; n < 2; ++n) _Pragma("unroll") for (int k = 0; k < 2; ++k) dst[n][k] = *(const LAS bf16x8*)(lds + PG8_SB(b, h) + boff + n * 2048 + k * 1024); } while (0)
; #define PG8_MMA(ai, bj, At, Bt) do { __builtin_amdgcn_s_setprio(1); _Pragma("unroll") for (int m = 0; m < 4; ++m) _Pragma("unroll") for (int n = 0; n < 2; ++n) _Pragma("unroll") for (int k = 0; k < 2; ++k) \
;         acc[ai][bj][m][n] = __builtin_amdgcn_mfma_f32_16x16x32_bf16(Bt[n][k], At[m][k], acc[ai][bj][m][n], 0, 0, 0); __builtin_amdgcn_s_setprio(0); } while (0)
; #define PG8_WAIT_V(n) asm volatile("s_waitcnt vmcnt(" #n ")" ::: "memory")
; #define PG8_WAIT_L(n) asm volatile("s_waitcnt lgkmcnt(" #n ")" ::: "memory")
; #define PG8_BAR __builtin_amdgcn_s_barrier()
; #define PG8_SCHED __builtin_amdgcn_sched_barrier(0)
; template <class Epi>
; __device__ __forceinline__ void gemm_phase(LAS unsigned char* lds, const Gemm g, const int G, const int cidx, const int tid, const Epi& E) {
;     ...
;             PG8_LDA(At, 0, 1); PG8_STAGE(PG8_SB(0, 0), b2, voffB); PG8_STAGE(PG8_SB(0, 1), b2 + hstepB, voffB); PG8_STAGE(PG8_SA(0, 0), a2, voffA);
;             PG8_WAIT_V(8); PG8_WAIT_L(0); PG8_BAR; PG8_MMA(1, 0, At, B0); PG8_MMA(1, 1, At, B1); PG8_BAR; PG8_SCHED;
;             PG8_LDB(B0, 1, 0); PG8_LDB(B1, 1, 1); PG8_SCHED; PG8_LDA(At, 1, 0); PG8_STAGE(PG8_SA(0, 1), a2 + hstepA, voffA);
;             PG8_WAIT_V(8); PG8_WAIT_L(0); PG8_BAR; PG8_MMA(0, 0, At, B0); PG8_MMA(0, 1, At, B1); PG8_BAR; PG8_SCHED;
.Lez_1:
	s_setprio 0
	s_barrier
	s_add_i32 s14, s66, s24
	v_lshl_add_u64 v[150:151], s[18:19], 0, v[152:153]
	s_mov_b32 m0, s14
	ds_read_b128 v[188:191], v145 offset:16384
	ds_read_b128 v[210:213], v145 offset:17408
	ds_read_b128 v[214:217], v145 offset:18432
	ds_read_b128 v[218:221], v145 offset:19456
	ds_read_b128 v[222:225], v145 offset:20480
	ds_read_b128 v[226:229], v145 offset:21504
	ds_read_b128 v[230:233], v145 offset:22528
	ds_read_b128 v[234:237], v145 offset:23552
	global_load_lds_dwordx4 v[150:151], off
	s_add_i32 m0, s14, 0x2000
	s_add_u32 s14, s18, 0x30000
	v_lshl_add_u64 v[192:193], s[18:19], 0, v[132:133]
	s_addc_u32 s15, s19, 0
	s_add_i32 s66, s67, s24
	global_load_lds_dwordx4 v[192:193], off
	v_lshl_add_u64 v[238:239], s[14:15], 0, v[152:153]
	s_mov_b32 m0, s66
	v_lshl_add_u64 v[240:241], s[52:53], 0, v[130:131]
	global_load_lds_dwordx4 v[238:239], off
	v_lshl_add_u64 v[238:239], s[14:15], 0, v[132:133]
	s_add_i32 m0, s66, 0x2000
	s_nop 0
	global_load_lds_dwordx4 v[238:239], off
	v_lshl_add_u64 v[238:239], s[52:53], 0, v[128:129]
	s_mov_b32 m0, s25
	s_nop 0
	global_load_lds_dwordx4 v[238:239], off
	s_mov_b32 m0, s29
	s_nop 0
	global_load_lds_dwordx4 v[240:241], off
	s_waitcnt vmcnt(8)
	s_waitcnt lgkmcnt(0)
	s_barrier
	s_setprio 1
	s_waitcnt lgkmcnt(0)
	s_cmp_gt_i32 s92, 0
	s_cbranch_scc1 .Lez_2
	v_mfma_f32_16x16x32_bf16 v[60:63], v[138:141], v[188:191], v[60:63]
	v_mfma_f32_16x16x32_bf16 v[56:59], v[164:167], v[188:191], v[56:59]
	v_mfma_f32_16x16x32_bf16 v[44:47], v[138:141], v[214:217], v[44:47]
	v_mfma_f32_16x16x32_bf16 v[40:43], v[164:167], v[214:217], v[40:43]
	v_mfma_f32_16x16x32_bf16 v[28:31], v[138:141], v[222:225], v[28:31]
	v_mfma_f32_16x16x32_bf16 v[24:27], v[164:167], v[222:225], v[24:27]
	v_mfma_f32_16x16x32_bf16 v[12:15], v[138:141], v[230:233], v[12:15]
	v_mfma_f32_16x16x32_bf16 v[8:11], v[164:167], v[230:233], v[8:11]
	v_mfma_f32_16x16x32_bf16 v[60:63], v[146:149], v[210:213], v[60:63]
	v_mfma_f32_16x16x32_bf16 v[56:59], v[168:171], v[210:213], v[56:59]
	v_mfma_f32_16x16x32_bf16 v[44:47], v[146:149], v[218:221], v[44:47]
	v_mfma_f32_16x16x32_bf16 v[40:43], v[168:171], v[218:221], v[40:43]
	v_mfma_f32_16x16x32_bf16 v[28:31], v[146:149], v[226:229], v[28:31]
	v_mfma_f32_16x16x32_bf16 v[24:27], v[168:171], v[226:229], v[24:27]
	v_mfma_f32_16x16x32_bf16 v[12:15], v[146:149], v[234:237], v[12:15]
	v_mfma_f32_16x16x32_bf16 v[8:11], v[168:171], v[234:237], v[8:11]
.Lez_2:
	s_setprio 0
	s_setprio 1
	s_cmp_lt_i32 s92, 2
	s_cbranch_scc1 .Lez_3
	v_mfma_f32_16x16x32_bf16 v[52:55], v[172:175], v[188:191], v[52:55]
	v_mfma_f32_16x16x32_bf16 v[48:51], v[180:183], v[188:191], v[48:51]
	v_mfma_f32_16x16x32_bf16 v[36:39], v[172:175], v[214:217], v[36:39]
	v_mfma_f32_16x16x32_bf16 v[32:35], v[180:183], v[214:217], v[32:35]
	v_mfma_f32_16x16x32_bf16 v[20:23], v[172:175], v[222:225], v[20:23]
	v_mfma_f32_16x16x32_bf16 v[16:19], v[180:183], v[222:225], v[16:19]
	v_mfma_f32_16x16x32_bf16 v[4:7], v[172:175], v[230:233], v[4:7]
	v_mfma_f32_16x16x32_bf16 v[0:3], v[180:183], v[230:233], v[0:3]
	v_mfma_f32_16x16x32_bf16 v[52:55], v[176:179], v[210:213], v[52:55]
	v_mfma_f32_16x16x32_bf16 v[48:51], v[184:187], v[210:213], v[48:51]
	v_mfma_f32_16x16x32_bf16 v[36:39], v[176:179], v[218:221], v[36:39]
	v_mfma_f32_16x16x32_bf16 v[32:35], v[184:187], v[218:221], v[32:35]
	v_mfma_f32_16x16x32_bf16 v[20:23], v[176:179], v[226:229], v[20:23]
	v_mfma_f32_16x16x32_bf16 v[16:19], v[184:187], v[226:229], v[16:19]
	v_mfma_f32_16x16x32_bf16 v[4:7], v[176:179], v[234:237], v[4:7]
	v_mfma_f32_16x16x32_bf16 v[0:3], v[184:187], v[234:237], v[0:3]
.Lez_3:
	s_setprio 0
	s_barrier
	s_add_i32 s66, 0, 0x18000
	v_add_u32_e32 v158, s66, v144
	s_add_i32 s67, 0, 0x1c000
	ds_read_b128 v[138:141], v158
	ds_read_b128 v[146:149], v158 offset:1024
	ds_read_b128 v[164:167], v158 offset:2048
	ds_read_b128 v[168:171], v158 offset:3072
	v_add_u32_e32 v158, s67, v144
	ds_read_b128 v[172:175], v158
	ds_read_b128 v[176:179], v158 offset:1024
	ds_read_b128 v[180:183], v158 offset:2048
	ds_read_b128 v[184:187], v158 offset:3072
	s_add_u32 s14, s52, 0x30000
	s_addc_u32 s15, s53, 0
	s_mov_b32 m0, s31
	v_lshl_add_u64 v[242:243], s[14:15], 0, v[128:129]
	ds_read_b128 v[188:191], v145 offset:32768
	ds_read_b128 v[210:213], v145 offset:33792
	ds_read_b128 v[214:217], v145 offset:34816
	ds_read_b128 v[218:221], v145 offset:35840
	ds_read_b128 v[222:225], v145 offset:36864
	ds_read_b128 v[226:229], v145 offset:37888
	ds_read_b128 v[230:233], v145 offset:38912
	ds_read_b128 v[234:237], v145 offset:39936
	global_load_lds_dwordx4 v[242:243], off
	v_lshl_add_u64 v[242:243], s[14:15], 0, v[130:131]
	s_mov_b32 m0, s54
	s_nop 0
	global_load_lds_dwordx4 v[242:243], off
	s_waitcnt vmcnt(8)
	s_waitcnt lgkmcnt(0)
	s_barrier
	s_setprio 1
	s_waitcnt lgkmcnt(0)
	s_cmp_gt_i32 s92, 0
	s_cbranch_scc1 .Lez_4
	v_mfma_f32_16x16x32_bf16 v[124:127], v[138:141], v[188:191], v[124:127]
	v_mfma_f32_16x16x32_bf16 v[120:123], v[164:167], v[188:191], v[120:123]
	v_mfma_f32_16x16x32_bf16 v[108:111], v[138:141], v[214:217], v[108:111]
	v_mfma_f32_16x16x32_bf16 v[104:107], v[164:167], v[214:217], v[104:107]
	v_mfma_f32_16x16x32_bf16 v[92:95], v[138:141], v[222:225], v[92:95]
	v_mfma_f32_16x16x32_bf16 v[88:91], v[164:167], v[222:225], v[88:91]
	v_mfma_f32_16x16x32_bf16 v[76:79], v[138:141], v[230:233], v[76:79]
	v_mfma_f32_16x16x32_bf16 v[72:75], v[164:167], v[230:233], v[72:75]
	v_mfma_f32_16x16x32_bf16 v[124:127], v[146:149], v[210:213], v[124:127]
	v_mfma_f32_16x16x32_bf16 v[120:123], v[168:171], v[210:213], v[120:123]
	v_mfma_f32_16x16x32_bf16 v[108:111], v[146:149], v[218:221], v[108:111]
	v_mfma_f32_16x16x32_bf16 v[104:107], v[168:171], v[218:221], v[104:107]
	v_mfma_f32_16x16x32_bf16 v[92:95], v[146:149], v[226:229], v[92:95]
	v_mfma_f32_16x16x32_bf16 v[88:91], v[168:171], v[226:229], v[88:91]
	v_mfma_f32_16x16x32_bf16 v[76:79], v[146:149], v[234:237], v[76:79]
	v_mfma_f32_16x16x32_bf16 v[72:75], v[168:171], v[234:237], v[72:75]

; #define PG8_STAGE(bufoff, gbase, voff) do { _Pragma("unroll") for (int _i = 0; _i < 2; ++_i) \
;         __builtin_amdgcn_global_load_lds((const unsigned*)((const char*)(gbase) + (voff)[_i]), (LAS unsigned*)(lds + (bufoff) + ldsw + _i * 8192), 16, 0, 0); } while (0)
; #define PG8_LDA(dst, b, h) do { _Pragma("unroll") for (int m = 0; m < 4; ++m) _Pragma("unroll") for (int k = 0; k < 2; ++k) dst[m][k] = *(const LAS bf16x8*)(lds + PG8_SA(b, h) + aoff + m * 2048 + k * 1024); } while (0)
; #define PG8_MMA(ai, bj, At, Bt) do { __builtin_amdgcn_s_setprio(1); _Pragma("unroll") for (int m = 0; m < 4; ++m) _Pragma("unroll") for (int n = 0; n < 2; ++n) _Pragma("unroll") for (int k = 0; k < 2; ++k) \
;         acc[ai][bj][m][n] = __builtin_amdgcn_mfma_f32_16x16x32_bf16(Bt[n][k], At[m][k], acc[ai][bj][m][n], 0, 0, 0); __builtin_amdgcn_s_setprio(0); } while (0)
; #define PG8_WAIT_V(n) asm volatile("s_waitcnt vmcnt(" #n ")" ::: "memory")
; #define PG8_WAIT_L(n) asm volatile("s_waitcnt lgkmcnt(" #n ")" ::: "memory")
; #define PG8_BAR __builtin_amdgcn_s_barrier()
; #define PG8_SCHED __builtin_amdgcn_sched_barrier(0)
; template <class Epi>
; __device__ __forceinline__ void gemm_phase(LAS unsigned char* lds, const Gemm g, const int G, const int cidx, const int tid, const Epi& E) {
;     ...
;             PG8_LDA(At, 1, 1); PG8_STAGE(PG8_SB(1, 0), b3, voffB); PG8_STAGE(PG8_SB(1, 1), b3 + hstepB, voffB); PG8_STAGE(PG8_SA(1, 0), a3, voffA);
;             PG8_WAIT_V(8); PG8_WAIT_L(0); PG8_BAR; PG8_MMA(1, 0, At, B0); PG8_MMA(1, 1, At, B1); PG8_BAR; PG8_SCHED;
.Lez_5:
	s_setprio 0
	s_barrier
	s_add_i32 s14, s66, s24
	v_lshl_add_u64 v[150:151], v[150:151], 0, s[96:97]
	s_mov_b32 m0, s14
	ds_read_b128 v[188:191], v145 offset:49152
	ds_read_b128 v[210:213], v145 offset:50176
	ds_read_b128 v[214:217], v145 offset:51200
	ds_read_b128 v[218:221], v145 offset:52224
	ds_read_b128 v[222:225], v145 offset:53248
	ds_read_b128 v[226:229], v145 offset:54272
	ds_read_b128 v[230:233], v145 offset:55296
	ds_read_b128 v[234:237], v145 offset:56320
	global_load_lds_dwordx4 v[150:151], off
	s_add_i32 m0, s14, 0x2000
	s_add_u32 s14, s18, 0x30080
	v_lshl_add_u64 v[150:151], v[192:193], 0, s[96:97]
	s_addc_u32 s15, s19, 0
	s_add_i32 s18, s67, s24
	global_load_lds_dwordx4 v[150:151], off
	v_lshl_add_u64 v[150:151], s[14:15], 0, v[152:153]
	s_mov_b32 m0, s18
	s_nop 0
	global_load_lds_dwordx4 v[150:151], off
	v_lshl_add_u64 v[150:151], s[14:15], 0, v[132:133]
	s_add_i32 m0, s18, 0x2000
	s_nop 0
	global_load_lds_dwordx4 v[150:151], off
	v_lshl_add_u64 v[150:151], v[238:239], 0, s[96:97]
	s_mov_b32 m0, s58
	s_nop 0
	global_load_lds_dwordx4 v[150:151], off
	v_lshl_add_u64 v[150:151], v[240:241], 0, s[96:97]
	s_mov_b32 m0, s59
	s_nop 0
	global_load_lds_dwordx4 v[150:151], off
	s_waitcnt vmcnt(8)
	s_waitcnt lgkmcnt(0)
	s_barrier
	s_setprio 1
	s_waitcnt lgkmcnt(0)
	s_cmp_gt_i32 s92, 0
	s_cbranch_scc1 .Lez_6
	v_mfma_f32_16x16x32_bf16 v[60:63], v[138:141], v[188:191], v[60:63]
	v_mfma_f32_16x16x32_bf16 v[56:59], v[164:167], v[188:191], v[56:59]
	v_mfma_f32_16x16x32_bf16 v[44:47], v[138:141], v[214:217], v[44:47]
	v_mfma_f32_16x16x32_bf16 v[40:43], v[164:167], v[214:217], v[40:43]
	v_mfma_f32_16x16x32_bf16 v[28:31], v[138:141], v[222:225], v[28:31]
	v_mfma_f32_16x16x32_bf16 v[24:27], v[164:167], v[222:225], v[24:27]
	v_mfma_f32_16x16x32_bf16 v[12:15], v[138:141], v[230:233], v[12:15]
	v_mfma_f32_16x16x32_bf16 v[8:11], v[164:167], v[230:233], v[8:11]
	v_mfma_f32_16x16x32_bf16 v[60:63], v[146:149], v[210:213], v[60:63]
	v_mfma_f32_16x16x32_bf16 v[56:59], v[168:171], v[210:213], v[56:59]
	v_mfma_f32_16x16x32_bf16 v[44:47], v[146:149], v[218:221], v[44:47]
	v_mfma_f32_16x16x32_bf16 v[40:43], v[168:171], v[218:221], v[40:43]
	v_mfma_f32_16x16x32_bf16 v[28:31], v[146:149], v[226:229], v[28:31]
	v_mfma_f32_16x16x32_bf16 v[24:27], v[168:171], v[226:229], v[24:27]
	v_mfma_f32_16x16x32_bf16 v[12:15], v[146:149], v[234:237], v[12:15]
	v_mfma_f32_16x16x32_bf16 v[8:11], v[168:171], v[234:237], v[8:11]

; #define PG8_MMA(ai, bj, At, Bt) do { __builtin_amdgcn_s_setprio(1); _Pragma("unroll") for (int m = 0; m < 4; ++m) _Pragma("unroll") for (int n = 0; n < 2; ++n) _Pragma("unroll") for (int k = 0; k < 2; ++k) \
;         acc[ai][bj][m][n] = __builtin_amdgcn_mfma_f32_16x16x32_bf16(Bt[n][k], At[m][k], acc[ai][bj][m][n], 0, 0, 0); __builtin_amdgcn_s_setprio(0); } while (0)
; #define PG8_WAIT_V(n) asm volatile("s_waitcnt vmcnt(" #n ")" ::: "memory")
; #define PG8_WAIT_L(n) asm volatile("s_waitcnt lgkmcnt(" #n ")" ::: "memory")
; #define PG8_BAR __builtin_amdgcn_s_barrier()
; #define PG8_SCHED __builtin_amdgcn_sched_barrier(0)
; template <class Epi>
; __device__ __forceinline__ void gemm_phase(LAS unsigned char* lds, const Gemm g, const int G, const int cidx, const int tid, const Epi& E) {
;     ...
;         for (int t = 0; t < nt; t += 2) {
;     ...
;             PG8_WAIT_V(8); PG8_WAIT_L(0); PG8_BAR; PG8_MMA(1, 0, At, B0); PG8_MMA(1, 1, At, B1); PG8_BAR; PG8_SCHED;
;         }
.Lez_7:
	s_setprio 0
	s_barrier
	s_add_i32 s92, s92, 2
	s_cmp_eq_u32 s92, 0
	s_cselect_b32 s66, 1, 0
	s_lshl_b32 s66, s66, 8
	s_add_i32 s66, s66, 0x100
	s_add_u32 s64, s64, s66
	s_addc_u32 s65, s65, 0
	s_cmp_gt_u32 s92, 5
	s_mov_b64 s[14:15], s[16:17]
	s_cbranch_scc0 .LBB0_509
	s_and_b64 vcc, exec, s[10:11]
	s_cbranch_vccz .LBB0_512
	s_barrier
